# final residual fold unrolled x4; attn0 window bias/mask as straight-line code with 16 LDS lookups in flight
# speedup vs baseline: 1.0639x; 1.0000x over previous
.LBB0_7:
	s_mov_b64 s[30:31], s[38:39]
	s_waitcnt lgkmcnt(0)
	s_load_dwordx2 s[28:29], s[30:31], 0x178
	s_mov_b64 s[40:41], 0xb0000
	s_mov_b64 s[6:7], -1
	s_mov_b64 s[0:1], 0
	s_cmp_lt_i32 s26, 45
	s_mov_b64 s[4:5], 0
	s_mov_b64 s[8:9], 0
	s_cbranch_scc1 .LBB0_13
	s_mov_b64 s[8:9], -1
	s_mov_b64 s[6:7], 0
	s_cmp_eq_u32 s26, 45
	s_cbranch_scc0 .LBB0_13
	s_mov_b32 s2, s87
	v_mov_b32_e32 v1, v0
	s_nop 0
	v_lshl_add_u32 v4, s2, 9, v1
	s_mov_b32 s2, 0x200000
	v_cmp_gt_i32_e32 vcc, s2, v4
	s_and_saveexec_b64 s[4:5], vcc
	s_cbranch_execz .LBB0_12
	s_load_dword s2, s[20:21], 0x0
	v_ashrrev_i32_e32 v5, 31, v4
	v_lshlrev_b64 v[6:7], 4, v[4:5]
	s_mov_b64 s[12:13], 0
	s_waitcnt lgkmcnt(0)
	s_lshl_b32 s8, s2, 9
	s_ashr_i32 s9, s8, 31
	s_lshl_b64 s[10:11], s[8:9], 4
	s_cmp_eq_u32 s8, 0x20000
	s_cbranch_scc0 .LBB0_11
	s_load_dwordx2 s[2:3], s[30:31], 0x170
	v_lshl_add_u64 v[12:13], s[28:29], 0, v[6:7]
	v_add_co_u32_e32 v12, vcc, 0x7020000, v12
	s_nop 1
	v_addc_co_u32_e32 v13, vcc, 0, v13, vcc
	s_waitcnt lgkmcnt(0)
	v_lshl_add_u64 v[16:17], s[2:3], 0, v[6:7]
	v_mov_b64_e32 v[52:53], v[16:17]
	global_load_dwordx4 v[20:23], v[16:17], off
	global_load_dwordx4 v[24:27], v[12:13], off
	v_lshl_add_u64 v[16:17], v[16:17], 0, s[10:11]
	v_lshl_add_u64 v[12:13], v[12:13], 0, s[10:11]
	v_mov_b64_e32 v[54:55], v[16:17]
	global_load_dwordx4 v[28:31], v[16:17], off
	global_load_dwordx4 v[32:35], v[12:13], off
	v_lshl_add_u64 v[16:17], v[16:17], 0, s[10:11]
	v_lshl_add_u64 v[12:13], v[12:13], 0, s[10:11]
	v_mov_b64_e32 v[56:57], v[16:17]
	global_load_dwordx4 v[36:39], v[16:17], off
	global_load_dwordx4 v[40:43], v[12:13], off
	v_lshl_add_u64 v[16:17], v[16:17], 0, s[10:11]
	v_lshl_add_u64 v[12:13], v[12:13], 0, s[10:11]
	v_mov_b64_e32 v[58:59], v[16:17]
	global_load_dwordx4 v[44:47], v[16:17], off
	global_load_dwordx4 v[48:51], v[12:13], off
	s_waitcnt vmcnt(6)
	v_pk_add_f32 v[20:21], v[20:21], v[24:25]
	v_pk_add_f32 v[22:23], v[22:23], v[26:27]
	global_store_dwordx4 v[52:53], v[20:23], off
	s_waitcnt vmcnt(5)
	v_pk_add_f32 v[28:29], v[28:29], v[32:33]
	v_pk_add_f32 v[30:31], v[30:31], v[34:35]
	global_store_dwordx4 v[54:55], v[28:31], off
	s_waitcnt vmcnt(4)
	v_pk_add_f32 v[36:37], v[36:37], v[40:41]
	v_pk_add_f32 v[38:39], v[38:39], v[42:43]
	global_store_dwordx4 v[56:57], v[36:39], off
	s_waitcnt vmcnt(3)
	v_pk_add_f32 v[44:45], v[44:45], v[48:49]
	v_pk_add_f32 v[46:47], v[46:47], v[50:51]
	global_store_dwordx4 v[58:59], v[44:47], off
	v_lshl_add_u64 v[16:17], v[16:17], 0, s[10:11]
	v_lshl_add_u64 v[12:13], v[12:13], 0, s[10:11]
	v_mov_b64_e32 v[52:53], v[16:17]
	global_load_dwordx4 v[20:23], v[16:17], off
	global_load_dwordx4 v[24:27], v[12:13], off
	v_lshl_add_u64 v[16:17], v[16:17], 0, s[10:11]
	v_lshl_add_u64 v[12:13], v[12:13], 0, s[10:11]
	v_mov_b64_e32 v[54:55], v[16:17]
	global_load_dwordx4 v[28:31], v[16:17], off
	global_load_dwordx4 v[32:35], v[12:13], off
	v_lshl_add_u64 v[16:17], v[16:17], 0, s[10:11]
	v_lshl_add_u64 v[12:13], v[12:13], 0, s[10:11]
	v_mov_b64_e32 v[56:57], v[16:17]
	global_load_dwordx4 v[36:39], v[16:17], off
	global_load_dwordx4 v[40:43], v[12:13], off
	v_lshl_add_u64 v[16:17], v[16:17], 0, s[10:11]
	v_lshl_add_u64 v[12:13], v[12:13], 0, s[10:11]
	v_mov_b64_e32 v[58:59], v[16:17]
	global_load_dwordx4 v[44:47], v[16:17], off
	global_load_dwordx4 v[48:51], v[12:13], off
	s_waitcnt vmcnt(6)
	v_pk_add_f32 v[20:21], v[20:21], v[24:25]
	v_pk_add_f32 v[22:23], v[22:23], v[26:27]
	global_store_dwordx4 v[52:53], v[20:23], off
	s_waitcnt vmcnt(5)
	v_pk_add_f32 v[28:29], v[28:29], v[32:33]
	v_pk_add_f32 v[30:31], v[30:31], v[34:35]
	global_store_dwordx4 v[54:55], v[28:31], off
	s_waitcnt vmcnt(4)
	v_pk_add_f32 v[36:37], v[36:37], v[40:41]
	v_pk_add_f32 v[38:39], v[38:39], v[42:43]
	global_store_dwordx4 v[56:57], v[36:39], off
	s_waitcnt vmcnt(3)
	v_pk_add_f32 v[44:45], v[44:45], v[48:49]
	v_pk_add_f32 v[46:47], v[46:47], v[50:51]
	global_store_dwordx4 v[58:59], v[44:47], off
	v_lshl_add_u64 v[16:17], v[16:17], 0, s[10:11]
	v_lshl_add_u64 v[12:13], v[12:13], 0, s[10:11]
	v_mov_b64_e32 v[52:53], v[16:17]
	global_load_dwordx4 v[20:23], v[16:17], off
	global_load_dwordx4 v[24:27], v[12:13], off
	v_lshl_add_u64 v[16:17], v[16:17], 0, s[10:11]
	v_lshl_add_u64 v[12:13], v[12:13], 0, s[10:11]
	v_mov_b64_e32 v[54:55], v[16:17]
	global_load_dwordx4 v[28:31], v[16:17], off
	global_load_dwordx4 v[32:35], v[12:13], off
	v_lshl_add_u64 v[16:17], v[16:17], 0, s[10:11]
	v_lshl_add_u64 v[12:13], v[12:13], 0, s[10:11]
	v_mov_b64_e32 v[56:57], v[16:17]
	global_load_dwordx4 v[36:39], v[16:17], off
	global_load_dwordx4 v[40:43], v[12:13], off
	v_lshl_add_u64 v[16:17], v[16:17], 0, s[10:11]
	v_lshl_add_u64 v[12:13], v[12:13], 0, s[10:11]
	v_mov_b64_e32 v[58:59], v[16:17]
	global_load_dwordx4 v[44:47], v[16:17], off
	global_load_dwordx4 v[48:51], v[12:13], off
	s_waitcnt vmcnt(6)
	v_pk_add_f32 v[20:21], v[20:21], v[24:25]
	v_pk_add_f32 v[22:23], v[22:23], v[26:27]
	global_store_dwordx4 v[52:53], v[20:23], off
	s_waitcnt vmcnt(5)
	v_pk_add_f32 v[28:29], v[28:29], v[32:33]
	v_pk_add_f32 v[30:31], v[30:31], v[34:35]
	global_store_dwordx4 v[54:55], v[28:31], off
	s_waitcnt vmcnt(4)
	v_pk_add_f32 v[36:37], v[36:37], v[40:41]
	v_pk_add_f32 v[38:39], v[38:39], v[42:43]
	global_store_dwordx4 v[56:57], v[36:39], off
	s_waitcnt vmcnt(3)
	v_pk_add_f32 v[44:45], v[44:45], v[48:49]
	v_pk_add_f32 v[46:47], v[46:47], v[50:51]
	global_store_dwordx4 v[58:59], v[44:47], off
	v_lshl_add_u64 v[16:17], v[16:17], 0, s[10:11]
	v_lshl_add_u64 v[12:13], v[12:13], 0, s[10:11]
	v_mov_b64_e32 v[52:53], v[16:17]
	global_load_dwordx4 v[20:23], v[16:17], off
	global_load_dwordx4 v[24:27], v[12:13], off
	v_lshl_add_u64 v[16:17], v[16:17], 0, s[10:11]
	v_lshl_add_u64 v[12:13], v[12:13], 0, s[10:11]
	v_mov_b64_e32 v[54:55], v[16:17]
	global_load_dwordx4 v[28:31], v[16:17], off
	global_load_dwordx4 v[32:35], v[12:13], off
	v_lshl_add_u64 v[16:17], v[16:17], 0, s[10:11]
	v_lshl_add_u64 v[12:13], v[12:13], 0, s[10:11]
	v_mov_b64_e32 v[56:57], v[16:17]
	global_load_dwordx4 v[36:39], v[16:17], off
	global_load_dwordx4 v[40:43], v[12:13], off
	v_lshl_add_u64 v[16:17], v[16:17], 0, s[10:11]
	v_lshl_add_u64 v[12:13], v[12:13], 0, s[10:11]
	v_mov_b64_e32 v[58:59], v[16:17]
	global_load_dwordx4 v[44:47], v[16:17], off
	global_load_dwordx4 v[48:51], v[12:13], off
	s_waitcnt vmcnt(6)
	v_pk_add_f32 v[20:21], v[20:21], v[24:25]
	v_pk_add_f32 v[22:23], v[22:23], v[26:27]
	global_store_dwordx4 v[52:53], v[20:23], off
	s_waitcnt vmcnt(5)
	v_pk_add_f32 v[28:29], v[28:29], v[32:33]
	v_pk_add_f32 v[30:31], v[30:31], v[34:35]
	global_store_dwordx4 v[54:55], v[28:31], off
	s_waitcnt vmcnt(4)
	v_pk_add_f32 v[36:37], v[36:37], v[40:41]
	v_pk_add_f32 v[38:39], v[38:39], v[42:43]
	global_store_dwordx4 v[56:57], v[36:39], off
	s_waitcnt vmcnt(3)
	v_pk_add_f32 v[44:45], v[44:45], v[48:49]
	v_pk_add_f32 v[46:47], v[46:47], v[50:51]
	global_store_dwordx4 v[58:59], v[44:47], off
	s_branch .LBB0_12

.LBB0_622:
	v_mov_b32_e32 v39, v3
	v_mul_u32_u24_e32 v133, s0, v154
	v_lshl_add_u64 v[114:115], v[38:39], 1, v[40:41]
	v_or_b32_e32 v38, v133, v156
	v_lshlrev_b32_e32 v38, 1, v38
	v_lshl_add_u64 v[116:117], v[114:115], 0, v[38:39]
	v_xor_b32_e32 v38, 0x80000000, v132
	v_mov_b32_e32 v39, v38
	v_mov_b32_e32 v40, v38
	v_mov_b32_e32 v41, v38
	v_mov_b32_e32 v42, v38
	v_mov_b32_e32 v43, v38
	v_mov_b32_e32 v44, v38
	v_mov_b32_e32 v45, v38
	v_mov_b32_e32 v46, v38
	v_mov_b32_e32 v47, v38
	v_mov_b32_e32 v48, v38
	v_mov_b32_e32 v49, v38
	v_mov_b32_e32 v50, v38
	v_mov_b32_e32 v51, v38
	v_mov_b32_e32 v52, v38
	v_mov_b32_e32 v53, v38
	s_lshl_b32 s1, s0, 5
	v_mov_b32_e32 v135, v3
	s_waitcnt vmcnt(11)
	v_mfma_f32_32x32x16_bf16 v[38:53], v[106:109], v[54:57], v[38:53]
	v_mov_b32_e32 v106, s1
	v_mad_u32_u24 v134, s0, v154, v106
	v_or_b32_e32 v106, v134, v156
	v_lshlrev_b32_e32 v106, 1, v106
	v_mov_b32_e32 v107, v3
	v_lshl_add_u64 v[106:107], v[114:115], 0, v[106:107]
	v_add_lshl_u32 v134, v134, v156, 1
	s_waitcnt vmcnt(10)
	v_mfma_f32_32x32x16_bf16 v[38:53], v[102:105], v[58:61], v[38:53]
	global_load_dwordx4 v[102:105], v[116:117], off
	s_nop 0
	global_load_dwordx4 v[106:109], v[106:107], off
	v_add_lshl_u32 v116, v133, v156, 1
	v_mov_b32_e32 v117, v3
	v_lshl_add_u64 v[116:117], v[114:115], 0, v[116:117]
	v_lshl_add_u64 v[114:115], v[114:115], 0, v[134:135]
	s_cmp_gt_u32 s15, 7
	s_cselect_b64 s[4:5], -1, 0
	s_waitcnt vmcnt(11)
	v_mfma_f32_32x32x16_bf16 v[38:53], v[110:113], v[62:65], v[38:53]
	global_load_dwordx4 v[110:113], v[116:117], off offset:32
	s_nop 0
	global_load_dwordx4 v[114:117], v[114:115], off offset:32
	s_and_b32 s14, s3, 32
	s_lshr_b32 s13, s12, 1
	s_cmp_lt_u32 s15, 8
	s_waitcnt vmcnt(12)
	v_mfma_f32_32x32x16_bf16 v[38:53], v[118:121], v[66:69], v[38:53]
	v_or_b32_e32 v118, s14, v174
	s_cbranch_scc1 .La0_nobias
	v_add_u32_e32 v236, s13, v131
	s_movk_i32 s15, 0x7c
	v_mul_lo_u32 v236, v236, s15
	v_add_u32_e32 v236, v151, v236
	v_mov_b32_e32 v237, 0xf149f2ca
	v_sub_u32_e32 v235, v118, v165
	v_add_u32_e32 v235, 15, v235
	v_med3_i32 v235, v235, 0, 30
	v_lshl_add_u32 v235, v235, 2, v236
	ds_read_b32 v188, v235 offset:868
	v_or_b32_e32 v234, 1, v118
	v_sub_u32_e32 v235, v234, v165
	v_add_u32_e32 v235, 15, v235
	v_med3_i32 v235, v235, 0, 30
	v_lshl_add_u32 v235, v235, 2, v236
	ds_read_b32 v189, v235 offset:868
	v_or_b32_e32 v234, 2, v118
	v_sub_u32_e32 v235, v234, v165
	v_add_u32_e32 v235, 15, v235
	v_med3_i32 v235, v235, 0, 30
	v_lshl_add_u32 v235, v235, 2, v236
	ds_read_b32 v190, v235 offset:868
	v_or_b32_e32 v234, 3, v118
	v_sub_u32_e32 v235, v234, v165
	v_add_u32_e32 v235, 15, v235
	v_med3_i32 v235, v235, 0, 30
	v_lshl_add_u32 v235, v235, 2, v236
	ds_read_b32 v191, v235 offset:868
	v_or_b32_e32 v234, 8, v118
	v_sub_u32_e32 v235, v234, v165
	v_add_u32_e32 v235, 15, v235
	v_med3_i32 v235, v235, 0, 30
	v_lshl_add_u32 v235, v235, 2, v236
	ds_read_b32 v192, v235 offset:868
	v_or_b32_e32 v234, 9, v118
	v_sub_u32_e32 v235, v234, v165
	v_add_u32_e32 v235, 15, v235
	v_med3_i32 v235, v235, 0, 30
	v_lshl_add_u32 v235, v235, 2, v236
	ds_read_b32 v193, v235 offset:868
	v_or_b32_e32 v234, 10, v118
	v_sub_u32_e32 v235, v234, v165
	v_add_u32_e32 v235, 15, v235
	v_med3_i32 v235, v235, 0, 30
	v_lshl_add_u32 v235, v235, 2, v236
	ds_read_b32 v194, v235 offset:868
	v_or_b32_e32 v234, 11, v118
	v_sub_u32_e32 v235, v234, v165
	v_add_u32_e32 v235, 15, v235
	v_med3_i32 v235, v235, 0, 30
	v_lshl_add_u32 v235, v235, 2, v236
	ds_read_b32 v195, v235 offset:868
	v_or_b32_e32 v234, 16, v118
	v_sub_u32_e32 v235, v234, v165
	v_add_u32_e32 v235, 15, v235
	v_med3_i32 v235, v235, 0, 30
	v_lshl_add_u32 v235, v235, 2, v236
	ds_read_b32 v196, v235 offset:868
	v_or_b32_e32 v234, 17, v118
	v_sub_u32_e32 v235, v234, v165
	v_add_u32_e32 v235, 15, v235
	v_med3_i32 v235, v235, 0, 30
	v_lshl_add_u32 v235, v235, 2, v236
	ds_read_b32 v197, v235 offset:868
	v_or_b32_e32 v234, 18, v118
	v_sub_u32_e32 v235, v234, v165
	v_add_u32_e32 v235, 15, v235
	v_med3_i32 v235, v235, 0, 30
	v_lshl_add_u32 v235, v235, 2, v236
	ds_read_b32 v198, v235 offset:868
	v_or_b32_e32 v234, 19, v118
	v_sub_u32_e32 v235, v234, v165
	v_add_u32_e32 v235, 15, v235
	v_med3_i32 v235, v235, 0, 30
	v_lshl_add_u32 v235, v235, 2, v236
	ds_read_b32 v199, v235 offset:868
	v_or_b32_e32 v234, 24, v118
	v_sub_u32_e32 v235, v234, v165
	v_add_u32_e32 v235, 15, v235
	v_med3_i32 v235, v235, 0, 30
	v_lshl_add_u32 v235, v235, 2, v236
	ds_read_b32 v200, v235 offset:868
	v_or_b32_e32 v234, 25, v118
	v_sub_u32_e32 v235, v234, v165
	v_add_u32_e32 v235, 15, v235
	v_med3_i32 v235, v235, 0, 30
	v_lshl_add_u32 v235, v235, 2, v236
	ds_read_b32 v201, v235 offset:868
	v_or_b32_e32 v234, 26, v118
	v_sub_u32_e32 v235, v234, v165
	v_add_u32_e32 v235, 15, v235
	v_med3_i32 v235, v235, 0, 30
	v_lshl_add_u32 v235, v235, 2, v236
	ds_read_b32 v202, v235 offset:868
	v_or_b32_e32 v234, 27, v118
	v_sub_u32_e32 v235, v234, v165
	v_add_u32_e32 v235, 15, v235
	v_med3_i32 v235, v235, 0, 30
	v_lshl_add_u32 v235, v235, 2, v236
	ds_read_b32 v203, v235 offset:868
	v_sub_u32_e32 v235, v118, v167
	v_cmp_gt_u32_e32 vcc, 16, v235
	s_waitcnt lgkmcnt(15)
	v_add_f32_e32 v38, v38, v188
	v_cndmask_b32_e32 v38, v237, v38, vcc
	v_or_b32_e32 v234, 1, v118
	v_sub_u32_e32 v235, v234, v167
	v_cmp_gt_u32_e32 vcc, 16, v235
	s_waitcnt lgkmcnt(14)
	v_add_f32_e32 v39, v39, v189
	v_cndmask_b32_e32 v39, v237, v39, vcc
	v_or_b32_e32 v234, 2, v118
	v_sub_u32_e32 v235, v234, v167
	v_cmp_gt_u32_e32 vcc, 16, v235
	s_waitcnt lgkmcnt(13)
	v_add_f32_e32 v40, v40, v190
	v_cndmask_b32_e32 v40, v237, v40, vcc
	v_or_b32_e32 v234, 3, v118
	v_sub_u32_e32 v235, v234, v167
	v_cmp_gt_u32_e32 vcc, 16, v235
	s_waitcnt lgkmcnt(12)
	v_add_f32_e32 v41, v41, v191
	v_cndmask_b32_e32 v41, v237, v41, vcc
	v_or_b32_e32 v234, 8, v118
	v_sub_u32_e32 v235, v234, v167
	v_cmp_gt_u32_e32 vcc, 16, v235
	s_waitcnt lgkmcnt(11)
	v_add_f32_e32 v42, v42, v192
	v_cndmask_b32_e32 v42, v237, v42, vcc
	v_or_b32_e32 v234, 9, v118
	v_sub_u32_e32 v235, v234, v167
	v_cmp_gt_u32_e32 vcc, 16, v235
	s_waitcnt lgkmcnt(10)
	v_add_f32_e32 v43, v43, v193
	v_cndmask_b32_e32 v43, v237, v43, vcc
	v_or_b32_e32 v234, 10, v118
	v_sub_u32_e32 v235, v234, v167
	v_cmp_gt_u32_e32 vcc, 16, v235
	s_waitcnt lgkmcnt(9)
	v_add_f32_e32 v44, v44, v194
	v_cndmask_b32_e32 v44, v237, v44, vcc
	v_or_b32_e32 v234, 11, v118
	v_sub_u32_e32 v235, v234, v167
	v_cmp_gt_u32_e32 vcc, 16, v235
	s_waitcnt lgkmcnt(8)
	v_add_f32_e32 v45, v45, v195
	v_cndmask_b32_e32 v45, v237, v45, vcc
	v_or_b32_e32 v234, 16, v118
	v_sub_u32_e32 v235, v234, v167
	v_cmp_gt_u32_e32 vcc, 16, v235
	s_waitcnt lgkmcnt(7)
	v_add_f32_e32 v46, v46, v196
	v_cndmask_b32_e32 v46, v237, v46, vcc
	v_or_b32_e32 v234, 17, v118
	v_sub_u32_e32 v235, v234, v167
	v_cmp_gt_u32_e32 vcc, 16, v235
	s_waitcnt lgkmcnt(6)
	v_add_f32_e32 v47, v47, v197
	v_cndmask_b32_e32 v47, v237, v47, vcc
	v_or_b32_e32 v234, 18, v118
	v_sub_u32_e32 v235, v234, v167
	v_cmp_gt_u32_e32 vcc, 16, v235
	s_waitcnt lgkmcnt(5)
	v_add_f32_e32 v48, v48, v198
	v_cndmask_b32_e32 v48, v237, v48, vcc
	v_or_b32_e32 v234, 19, v118
	v_sub_u32_e32 v235, v234, v167
	v_cmp_gt_u32_e32 vcc, 16, v235
	s_waitcnt lgkmcnt(4)
	v_add_f32_e32 v49, v49, v199
	v_cndmask_b32_e32 v49, v237, v49, vcc
	v_or_b32_e32 v234, 24, v118
	v_sub_u32_e32 v235, v234, v167
	v_cmp_gt_u32_e32 vcc, 16, v235
	s_waitcnt lgkmcnt(3)
	v_add_f32_e32 v50, v50, v200
	v_cndmask_b32_e32 v50, v237, v50, vcc
	v_or_b32_e32 v234, 25, v118
	v_sub_u32_e32 v235, v234, v167
	v_cmp_gt_u32_e32 vcc, 16, v235
	s_waitcnt lgkmcnt(2)
	v_add_f32_e32 v51, v51, v201
	v_cndmask_b32_e32 v51, v237, v51, vcc
	v_or_b32_e32 v234, 26, v118
	v_sub_u32_e32 v235, v234, v167
	v_cmp_gt_u32_e32 vcc, 16, v235
	s_waitcnt lgkmcnt(1)
	v_add_f32_e32 v52, v52, v202
	v_cndmask_b32_e32 v52, v237, v52, vcc
	v_or_b32_e32 v234, 27, v118
	v_sub_u32_e32 v235, v234, v167
	v_cmp_gt_u32_e32 vcc, 16, v235
	s_waitcnt lgkmcnt(0)
	v_add_f32_e32 v53, v53, v203
	v_cndmask_b32_e32 v53, v237, v53, vcc
	s_branch .LBB0_686
.La0_nobias:
	s_nop 11
